# in-proj output P stored write-through (sc1)
# baseline (speedup 1.0000x reference)
; __device__ __forceinline__ unsigned cvt_pk_bf16(float lo, float hi) { unsigned r; asm volatile("v_cvt_pk_bf16_f32 %0, %1, %2" : "=v"(r) : "v"(lo), "v"(hi)); return r; }
;     __device__ __forceinline__ void operator()(const f32x4 (&acc)[2][2][4][2], const Unit& u, int wr, int wc, int fr, int fq) const {
;     ...
;             for (int m = 0; m < 4; ++m) { bf16_t* rowp = base + (size_t)(row0 + ai * HALF + m * 16) * ldc + col0;
; #pragma unroll
;                 for (int bj = 0; bj < 2; ++bj) { f32x4 v0 = acc[ai][bj][m][0] + bv[bj][0], v1 = acc[ai][bj][m][1] + bv[bj][1];
;                     if (ACT == 1) { f32x2 a = gelu_pk((f32x2){v0[0], v0[1]}), b = gelu_pk((f32x2){v0[2], v0[3]}), c = gelu_pk((f32x2){v1[0], v1[1]}), d = gelu_pk((f32x2){v1[2], v1[3]});
;                         v0 = (f32x4){a.x, a.y, b.x, b.y}; v1 = (f32x4){c.x, c.y, d.x, d.y}; }
;                     v0 = v0 * sc; v1 = v1 * sc; u32x4 w; w.x = cvt_pk_bf16(v0[0], v0[1]); w.y = cvt_pk_bf16(v0[2], v0[3]); w.z = cvt_pk_bf16(v1[0], v1[1]); w.w = cvt_pk_bf16(v1[2], v1[3]);
;                     *(u32x4*)(rowp + bj * HALF) = w; } }
.LBB0_1101:
	v_lshl_or_b32 v138, s50, 8, v143
	v_readlane_b32 s24, v252, 60
	v_ashrrev_i32_e32 v139, 31, v138
	v_readlane_b32 s25, v252, 61
	v_lshl_add_u32 v145, s52, 8, v141
	s_movk_i32 s11, 0x1600
	v_lshl_add_u64 v[138:139], v[138:139], 1, s[24:25]
	v_pk_add_f32 v[146:147], v[126:127], 0 op_sel_hi:[1,0]
	v_mad_i64_i32 v[150:151], s[24:25], v145, s11, v[138:139]
	v_pk_add_f32 v[148:149], v[128:129], 0 op_sel_hi:[1,0]
	v_cvt_pk_bf16_f32 v146, v146, v147
	v_pk_add_f32 v[152:153], v[124:125], 0 op_sel_hi:[1,0]
	v_cvt_pk_bf16_f32 v147, v148, v149
	v_pk_add_f32 v[154:155], v[122:123], 0 op_sel_hi:[1,0]
	s_andn2_b64 vcc, exec, s[22:23]
	v_cvt_pk_bf16_f32 v148, v154, v155
	v_cvt_pk_bf16_f32 v149, v152, v153
	global_store_dwordx4 v[150:151], v[146:149], off sc1
	v_pk_add_f32 v[152:153], v[92:93], 0 op_sel_hi:[1,0]
	v_pk_add_f32 v[154:155], v[90:91], 0 op_sel_hi:[1,0]
	v_pk_add_f32 v[146:147], v[94:95], 0 op_sel_hi:[1,0]
	v_pk_add_f32 v[148:149], v[96:97], 0 op_sel_hi:[1,0]
	v_cvt_pk_bf16_f32 v146, v146, v147
	s_nop 0
	v_cvt_pk_bf16_f32 v147, v148, v149
	v_cvt_pk_bf16_f32 v148, v154, v155
	v_cvt_pk_bf16_f32 v149, v152, v153
	global_store_dwordx4 v[150:151], v[146:149], off offset:256 sc1
	v_pk_add_f32 v[152:153], v[116:117], 0 op_sel_hi:[1,0]
	v_pk_add_f32 v[154:155], v[114:115], 0 op_sel_hi:[1,0]
	v_or_b32_e32 v146, 16, v145
	v_mad_i64_i32 v[150:151], s[24:25], v146, s11, v[138:139]
	v_pk_add_f32 v[146:147], v[118:119], 0 op_sel_hi:[1,0]
	v_pk_add_f32 v[148:149], v[120:121], 0 op_sel_hi:[1,0]
	v_cvt_pk_bf16_f32 v146, v146, v147
	s_nop 0
	v_cvt_pk_bf16_f32 v147, v148, v149
	v_cvt_pk_bf16_f32 v148, v154, v155
	v_cvt_pk_bf16_f32 v149, v152, v153
	global_store_dwordx4 v[150:151], v[146:149], off sc1
	v_pk_add_f32 v[152:153], v[84:85], 0 op_sel_hi:[1,0]
	v_pk_add_f32 v[154:155], v[82:83], 0 op_sel_hi:[1,0]
	v_pk_add_f32 v[146:147], v[86:87], 0 op_sel_hi:[1,0]
	v_pk_add_f32 v[148:149], v[88:89], 0 op_sel_hi:[1,0]
	v_cvt_pk_bf16_f32 v146, v146, v147
	s_nop 0
	v_cvt_pk_bf16_f32 v147, v148, v149
	v_cvt_pk_bf16_f32 v148, v154, v155
	v_cvt_pk_bf16_f32 v149, v152, v153
	global_store_dwordx4 v[150:151], v[146:149], off offset:256 sc1
	v_pk_add_f32 v[152:153], v[108:109], 0 op_sel_hi:[1,0]
	v_pk_add_f32 v[154:155], v[106:107], 0 op_sel_hi:[1,0]
	v_or_b32_e32 v146, 32, v145
	v_mad_i64_i32 v[150:151], s[24:25], v146, s11, v[138:139]
	v_pk_add_f32 v[146:147], v[110:111], 0 op_sel_hi:[1,0]
	v_pk_add_f32 v[148:149], v[112:113], 0 op_sel_hi:[1,0]
	v_cvt_pk_bf16_f32 v146, v146, v147
	s_nop 0
	v_cvt_pk_bf16_f32 v147, v148, v149
	v_cvt_pk_bf16_f32 v148, v154, v155
	v_cvt_pk_bf16_f32 v149, v152, v153
	global_store_dwordx4 v[150:151], v[146:149], off sc1
	v_pk_add_f32 v[152:153], v[76:77], 0 op_sel_hi:[1,0]
	v_pk_add_f32 v[154:155], v[74:75], 0 op_sel_hi:[1,0]
	v_pk_add_f32 v[146:147], v[78:79], 0 op_sel_hi:[1,0]
	v_pk_add_f32 v[148:149], v[80:81], 0 op_sel_hi:[1,0]
	v_cvt_pk_bf16_f32 v146, v146, v147
	s_nop 0
	v_cvt_pk_bf16_f32 v147, v148, v149
	v_cvt_pk_bf16_f32 v148, v154, v155
	v_cvt_pk_bf16_f32 v149, v152, v153
	global_store_dwordx4 v[150:151], v[146:149], off offset:256 sc1
	v_pk_add_f32 v[152:153], v[100:101], 0 op_sel_hi:[1,0]
	v_pk_add_f32 v[154:155], v[98:99], 0 op_sel_hi:[1,0]
	v_or_b32_e32 v146, 48, v145
	v_mad_i64_i32 v[150:151], s[24:25], v146, s11, v[138:139]
	v_pk_add_f32 v[146:147], v[102:103], 0 op_sel_hi:[1,0]
	v_pk_add_f32 v[148:149], v[104:105], 0 op_sel_hi:[1,0]
	v_cvt_pk_bf16_f32 v146, v146, v147
	s_nop 0
	v_cvt_pk_bf16_f32 v147, v148, v149
	v_cvt_pk_bf16_f32 v148, v154, v155
	v_cvt_pk_bf16_f32 v149, v152, v153
	global_store_dwordx4 v[150:151], v[146:149], off sc1
	v_pk_add_f32 v[152:153], v[68:69], 0 op_sel_hi:[1,0]
	v_pk_add_f32 v[154:155], v[66:67], 0 op_sel_hi:[1,0]
	v_pk_add_f32 v[146:147], v[70:71], 0 op_sel_hi:[1,0]
	v_pk_add_f32 v[148:149], v[72:73], 0 op_sel_hi:[1,0]
	v_cvt_pk_bf16_f32 v146, v146, v147
	s_nop 0
	v_cvt_pk_bf16_f32 v147, v148, v149
	v_cvt_pk_bf16_f32 v148, v154, v155
	v_cvt_pk_bf16_f32 v149, v152, v153
; __device__ __forceinline__ unsigned cvt_pk_bf16(float lo, float hi) { unsigned r; asm volatile("v_cvt_pk_bf16_f32 %0, %1, %2" : "=v"(r) : "v"(lo), "v"(hi)); return r; }
; #define PG8_BAR __builtin_amdgcn_s_barrier()
;     __device__ __forceinline__ void operator()(const f32x4 (&acc)[2][2][4][2], const Unit& u, int wr, int wc, int fr, int fq) const {
;     ...
;             for (int m = 0; m < 4; ++m) { bf16_t* rowp = base + (size_t)(row0 + ai * HALF + m * 16) * ldc + col0;
; #pragma unroll
;                 for (int bj = 0; bj < 2; ++bj) { f32x4 v0 = acc[ai][bj][m][0] + bv[bj][0], v1 = acc[ai][bj][m][1] + bv[bj][1];
;                     if (ACT == 1) { f32x2 a = gelu_pk((f32x2){v0[0], v0[1]}), b = gelu_pk((f32x2){v0[2], v0[3]}), c = gelu_pk((f32x2){v1[0], v1[1]}), d = gelu_pk((f32x2){v1[2], v1[3]});
;                         v0 = (f32x4){a.x, a.y, b.x, b.y}; v1 = (f32x4){c.x, c.y, d.x, d.y}; }
;                     v0 = v0 * sc; v1 = v1 * sc; u32x4 w; w.x = cvt_pk_bf16(v0[0], v0[1]); w.y = cvt_pk_bf16(v0[2], v0[3]); w.z = cvt_pk_bf16(v1[0], v1[1]); w.w = cvt_pk_bf16(v1[2], v1[3]);
;                     *(u32x4*)(rowp + bj * HALF) = w; } }
;     ...
;         if (!has_next) break;
; #pragma unroll
;         for (int a = 0; a < 2; ++a)
; #pragma unroll
;             for (int b = 0; b < 2; ++b)
; #pragma unroll
;                 for (int m = 0; m < 4; ++m)
; #pragma unroll
;                     for (int n = 0; n < 2; ++n) acc[a][b][m][n] = (f32x4){0.f, 0.f, 0.f, 0.f};
;         cur = nxt; cA = nA; cB = nB; ++ui;
;         if constexpr (ALIGN_EPI) { if (wr == 1) PG8_BAR; }
	global_store_dwordx4 v[150:151], v[146:149], off offset:256 sc1
	v_pk_add_f32 v[152:153], v[60:61], 0 op_sel_hi:[1,0]
	v_pk_add_f32 v[154:155], v[58:59], 0 op_sel_hi:[1,0]
	v_add_u32_e32 v146, 0x80, v145
	v_mad_i64_i32 v[150:151], s[24:25], v146, s11, v[138:139]
	v_pk_add_f32 v[146:147], v[62:63], 0 op_sel_hi:[1,0]
	v_pk_add_f32 v[148:149], v[64:65], 0 op_sel_hi:[1,0]
	v_cvt_pk_bf16_f32 v146, v146, v147
	s_nop 0
	v_cvt_pk_bf16_f32 v147, v148, v149
	v_cvt_pk_bf16_f32 v148, v154, v155
	v_cvt_pk_bf16_f32 v149, v152, v153
	global_store_dwordx4 v[150:151], v[146:149], off sc1
	v_pk_add_f32 v[152:153], v[28:29], 0 op_sel_hi:[1,0]
	v_pk_add_f32 v[154:155], v[26:27], 0 op_sel_hi:[1,0]
	v_pk_add_f32 v[146:147], v[30:31], 0 op_sel_hi:[1,0]
	v_pk_add_f32 v[148:149], v[32:33], 0 op_sel_hi:[1,0]
	v_cvt_pk_bf16_f32 v146, v146, v147
	s_nop 0
	v_cvt_pk_bf16_f32 v147, v148, v149
	v_cvt_pk_bf16_f32 v148, v154, v155
	v_cvt_pk_bf16_f32 v149, v152, v153
	global_store_dwordx4 v[150:151], v[146:149], off offset:256 sc1
	v_pk_add_f32 v[152:153], v[52:53], 0 op_sel_hi:[1,0]
	v_pk_add_f32 v[154:155], v[50:51], 0 op_sel_hi:[1,0]
	v_add_u32_e32 v146, 0x90, v145
	v_mad_i64_i32 v[150:151], s[24:25], v146, s11, v[138:139]
	v_pk_add_f32 v[146:147], v[54:55], 0 op_sel_hi:[1,0]
	v_pk_add_f32 v[148:149], v[56:57], 0 op_sel_hi:[1,0]
	v_cvt_pk_bf16_f32 v146, v146, v147
	s_nop 0
	v_cvt_pk_bf16_f32 v147, v148, v149
	v_cvt_pk_bf16_f32 v148, v154, v155
	v_cvt_pk_bf16_f32 v149, v152, v153
	global_store_dwordx4 v[150:151], v[146:149], off sc1
	v_pk_add_f32 v[152:153], v[20:21], 0 op_sel_hi:[1,0]
	v_pk_add_f32 v[154:155], v[18:19], 0 op_sel_hi:[1,0]
	v_pk_add_f32 v[146:147], v[22:23], 0 op_sel_hi:[1,0]
	v_pk_add_f32 v[148:149], v[24:25], 0 op_sel_hi:[1,0]
	v_cvt_pk_bf16_f32 v146, v146, v147
	s_nop 0
	v_cvt_pk_bf16_f32 v147, v148, v149
	v_cvt_pk_bf16_f32 v148, v154, v155
	v_cvt_pk_bf16_f32 v149, v152, v153
	global_store_dwordx4 v[150:151], v[146:149], off offset:256 sc1
	v_pk_add_f32 v[152:153], v[44:45], 0 op_sel_hi:[1,0]
	v_pk_add_f32 v[154:155], v[42:43], 0 op_sel_hi:[1,0]
	v_add_u32_e32 v146, 0xa0, v145
	v_mad_i64_i32 v[150:151], s[24:25], v146, s11, v[138:139]
	v_pk_add_f32 v[148:149], v[48:49], 0 op_sel_hi:[1,0]
	v_pk_add_f32 v[146:147], v[46:47], 0 op_sel_hi:[1,0]
	v_add_u32_e32 v145, 0xb0, v145
	v_cvt_pk_bf16_f32 v146, v146, v147
	v_cvt_pk_bf16_f32 v147, v148, v149
	v_cvt_pk_bf16_f32 v148, v154, v155
	v_cvt_pk_bf16_f32 v149, v152, v153
	global_store_dwordx4 v[150:151], v[146:149], off sc1
	v_pk_add_f32 v[152:153], v[12:13], 0 op_sel_hi:[1,0]
	v_pk_add_f32 v[154:155], v[10:11], 0 op_sel_hi:[1,0]
	v_pk_add_f32 v[148:149], v[16:17], 0 op_sel_hi:[1,0]
	v_pk_add_f32 v[146:147], v[14:15], 0 op_sel_hi:[1,0]
	v_mad_i64_i32 v[138:139], s[24:25], v145, s11, v[138:139]
	v_cvt_pk_bf16_f32 v146, v146, v147
	v_cvt_pk_bf16_f32 v147, v148, v149
	v_cvt_pk_bf16_f32 v148, v154, v155
	v_cvt_pk_bf16_f32 v149, v152, v153
	global_store_dwordx4 v[150:151], v[146:149], off offset:256 sc1
	v_pk_add_f32 v[150:151], v[36:37], 0 op_sel_hi:[1,0]
	v_pk_add_f32 v[152:153], v[34:35], 0 op_sel_hi:[1,0]
	v_pk_add_f32 v[148:149], v[40:41], 0 op_sel_hi:[1,0]
	v_pk_add_f32 v[146:147], v[38:39], 0 op_sel_hi:[1,0]
	s_movk_i32 s24, 0x410
	v_cvt_pk_bf16_f32 v146, v146, v147
	v_cvt_pk_bf16_f32 v147, v148, v149
	v_cvt_pk_bf16_f32 v148, v152, v153
	v_cvt_pk_bf16_f32 v149, v150, v151
	global_store_dwordx4 v[138:139], v[146:149], off sc1
	v_pk_add_f32 v[150:151], v[4:5], 0 op_sel_hi:[1,0]
	v_pk_add_f32 v[152:153], v[2:3], 0 op_sel_hi:[1,0]
	v_pk_add_f32 v[148:149], v[8:9], 0 op_sel_hi:[1,0]
	v_pk_add_f32 v[146:147], v[6:7], 0 op_sel_hi:[1,0]
	s_nop 0
	v_cvt_pk_bf16_f32 v146, v146, v147
	v_cvt_pk_bf16_f32 v147, v148, v149
	v_cvt_pk_bf16_f32 v148, v152, v153
	v_cvt_pk_bf16_f32 v149, v150, v151
	global_store_dwordx4 v[138:139], v[146:149], off offset:256 sc1
	s_cbranch_vccnz .LBB0_1068
	s_andn2_b64 vcc, exec, s[6:7]
	s_cbranch_vccnz .LBB0_1067
	s_barrier
	s_branch .LBB0_1067
